# grid barrier: acquire-side buffer_inv issued at arrival (overlapped with the release wait) instead of after release; redundant invalidates dropped from the fused hand-off polls; on v21
# speedup vs baseline: 1.0139x; 1.0139x over previous
.LBB0_329:
	v_readlane_b32 s3, v254, 41
	s_add_u32 s26, s4, s3
	s_addc_u32 s3, s5, 0
	v_mov_b32_e32 v1, s26
	v_add_co_u32_e32 v6, vcc, 0x1000, v1
	v_mov_b32_e32 v1, s3
	s_nop 0
	v_addc_co_u32_e32 v7, vcc, 0, v1, vcc
	flat_atomic_add v1, v[6:7], v223 offset:1024 sc0
	v_cvt_f32_u32_e32 v3, v4
	v_sub_u32_e32 v5, 0, v4
	v_rcp_iflag_f32_e32 v3, v3
	s_nop 0
	v_mul_f32_e32 v3, 0x4f7ffffe, v3
	v_cvt_u32_f32_e32 v3, v3
	v_mul_lo_u32 v5, v5, v3
	v_mul_hi_u32 v5, v3, v5
	v_add_u32_e32 v3, v3, v5
	s_waitcnt vmcnt(0) lgkmcnt(0)
	v_mul_hi_u32 v3, v1, v3
	v_mul_lo_u32 v5, v3, v4
	v_add_u32_e32 v6, 1, v1
	v_sub_u32_e32 v1, v1, v5
	v_add_u32_e32 v7, 1, v3
	v_cmp_ge_u32_e32 vcc, v1, v4
	v_sub_u32_e32 v5, v1, v4
	s_nop 0
	v_cndmask_b32_e32 v3, v3, v7, vcc
	v_cndmask_b32_e32 v1, v1, v5, vcc
	v_add_u32_e32 v5, 1, v3
	v_cmp_ge_u32_e32 vcc, v1, v4
	s_nop 1
	v_cndmask_b32_e32 v1, v3, v5, vcc
	v_mad_u64_u32 v[4:5], s[6:7], v4, v1, v[4:5]
	v_cmp_ne_u32_e32 vcc, v6, v4
	s_and_saveexec_b64 s[6:7], vcc
	s_xor_b64 s[6:7], exec, s[6:7]
	s_cbranch_execz .LBB0_342
	buffer_inv sc1
	v_add_u32_e32 v8, 1, v1
	v_mul_lo_u32 v8, v8, v2
	v_mov_b32_e32 v2, s4
	v_add_co_u32_e32 v2, vcc, 0x3000, v2
	v_mov_b32_e32 v3, s5
	s_nop 0
	v_addc_co_u32_e32 v3, vcc, 0, v3, vcc
	flat_load_dword v2, v[2:3] offset:1024 sc1
	s_add_u32 s10, s4, 0x3400
	s_addc_u32 s11, s5, 0
	s_waitcnt vmcnt(0) lgkmcnt(0)
	v_cmp_lt_u32_e32 vcc, v2, v8
	s_and_saveexec_b64 s[8:9], vcc
	s_cbranch_execz .LBB0_341
	s_mov_b32 s27, 1
	s_mov_b64 s[12:13], 0
	s_branch .LBB0_333

.LBB0_341:
	s_or_b64 exec, exec, s[8:9]
	s_waitcnt vmcnt(0) lgkmcnt(0)
	s_waitcnt vmcnt(0)
.LBB0_342:
	s_andn2_saveexec_b64 s[6:7], s[6:7]
	s_cbranch_execz .LBB0_358
	v_mov_b32_e32 v1, s4
	v_add_co_u32_e32 v4, vcc, 0x3000, v1
	v_mov_b32_e32 v1, s5
	buffer_wbl2 sc1
	s_waitcnt vmcnt(0)
	v_addc_co_u32_e32 v5, vcc, 0, v1, vcc
	flat_atomic_add v1, v[4:5], v223 offset:1024 sc0
	buffer_inv sc1
	v_cvt_f32_u32_e32 v3, v2
	v_sub_u32_e32 v4, 0, v2
	s_add_u32 s6, s4, 0x3400
	s_addc_u32 s7, s5, 0
	v_rcp_iflag_f32_e32 v3, v3
	s_mov_b64 s[10:11], 0
	v_mul_f32_e32 v3, 0x4f7ffffe, v3
	v_cvt_u32_f32_e32 v3, v3
	v_mul_lo_u32 v4, v4, v3
	v_mul_hi_u32 v4, v3, v4
	v_add_u32_e32 v3, v3, v4
	s_waitcnt vmcnt(0) lgkmcnt(0)
	v_mul_hi_u32 v3, v1, v3
	v_mul_lo_u32 v5, v3, v2
	v_add_u32_e32 v4, 1, v1
	v_sub_u32_e32 v1, v1, v5
	v_add_u32_e32 v6, 1, v3
	v_cmp_ge_u32_e32 vcc, v1, v2
	v_sub_u32_e32 v5, v1, v2
	s_nop 0
	v_cndmask_b32_e32 v3, v3, v6, vcc
	v_cndmask_b32_e32 v1, v1, v5, vcc
	v_add_u32_e32 v5, 1, v3
	v_cmp_ge_u32_e32 vcc, v1, v2
	s_nop 1
	v_cndmask_b32_e32 v1, v3, v5, vcc
	v_mad_u64_u32 v[2:3], s[8:9], v2, v1, v[2:3]
	v_mov_b32_e32 v8, v2
	v_cmp_ne_u32_e32 vcc, v4, v2
	v_mov_b64_e32 v[2:3], s[6:7]
	s_and_saveexec_b64 s[8:9], vcc
	s_cbranch_execz .LBB0_355
	v_mov_b64_e32 v[2:3], s[6:7]
	flat_load_dword v2, v[2:3] sc1
	s_mov_b64 s[14:15], 0
	s_waitcnt vmcnt(0) lgkmcnt(0)
	v_cmp_lt_u32_e32 vcc, v2, v8
	s_and_saveexec_b64 s[12:13], vcc
	s_cbranch_execz .LBB0_354
	s_add_u32 s10, s4, 0x200
	s_addc_u32 s11, s5, 0
	s_mov_b32 s24, 1
	s_mov_b64 s[4:5], 0
	s_branch .LBB0_347

.LBB0_357:
	s_or_b64 exec, exec, s[4:5]
	v_mov_b32_e32 v1, s26
	v_add_co_u32_e32 v2, vcc, 0x2000, v1
	v_mov_b32_e32 v1, s3
	s_nop 0
	v_addc_co_u32_e32 v3, vcc, 0, v1, vcc
	s_waitcnt vmcnt(0) lgkmcnt(0)
	s_waitcnt vmcnt(0)

.Lpanel_poll:
	global_load_dword v85, v84, s[90:91] sc1
	s_waitcnt vmcnt(0)
	v_readfirstlane_b32 s17, v85
	s_cmp_ge_u32 s17, s19
	s_cbranch_scc1 .Lpanel_ready
	s_sleep 4
	s_add_u32 s18, s18, 1
	s_cmp_lt_u32 s18, 0x1000
	s_cbranch_scc1 .Lpanel_poll
.Lpanel_ready:
	s_waitcnt vmcnt(0)
.Lpanel_bar:
	s_barrier

.Ltail_poll:
	global_load_dword v3, v2, s[90:91] sc1
	s_waitcnt vmcnt(0)
	v_readfirstlane_b32 s16, v3
	s_cmp_ge_u32 s16, s17
	s_cbranch_scc1 .Ltail_ready
	s_sleep 4
	s_add_u32 s18, s18, 1
	s_cmp_lt_u32 s18, 0x1000
	s_cbranch_scc1 .Ltail_poll
.Ltail_ready:
	s_waitcnt vmcnt(0)
.Ltail_bar:
	s_barrier
